# pool group 3 (window 16): trailing-window sums moved to the matrix cores (transposed LDS reads x 0/1 band, f32 accumulate), then fma(S,1/cnt,-x)
# speedup vs baseline: 1.0105x; 1.0008x over previous
.LBB0_124:
	s_cmp_lg_u32 s42, 0x1c0000
	s_cselect_b32 s0, s11, 7
	s_add_i32 s0, s0, s10
	s_lshl_b32 s0, s0, 6
	s_and_b32 s2, s0, 0xfc0
	s_and_b32 s0, s0, 0xfffff000
	s_ashr_i32 s1, s0, 31
	v_add_u32_e32 v84, s2, v144
	s_lshl_b64 s[0:1], s[0:1], 11
	v_ashrrev_i32_e32 v85, 31, v84
	v_lshl_add_u64 v[82:83], v[138:139], 0, s[0:1]
	v_lshlrev_b64 v[84:85], 11, v[84:85]
	s_waitcnt lgkmcnt(0)
	s_barrier
	v_readfirstlane_b32 s66, v157
	v_readfirstlane_b32 s67, v186
	v_and_b32_e32 v226, 15, v186
	v_bfe_u32 v134, v186, 4, 2
	v_bfe_u32 v135, v186, 2, 2
	v_and_b32_e32 v136, 3, v186
	v_lshrrev_b32_e32 v137, 6, v186
	s_lshr_b32 s67, s67, 3
	s_sub_i32 s66, s66, s67
	v_lshl_add_u64 v[84:85], v[82:83], 0, v[84:85]
	global_load_dwordx4 v[102:105], v[84:85], off offset:1536
	v_add_u32_e32 v84, s2, v145
	v_ashrrev_i32_e32 v85, 31, v84
	v_lshlrev_b64 v[84:85], 11, v[84:85]
	v_lshl_add_u64 v[84:85], v[82:83], 0, v[84:85]
	global_load_dwordx4 v[106:109], v[84:85], off offset:1536
	v_add_u32_e32 v84, s2, v146
	v_ashrrev_i32_e32 v85, 31, v84
	v_lshlrev_b64 v[84:85], 11, v[84:85]
	v_lshl_add_u64 v[84:85], v[82:83], 0, v[84:85]
	global_load_dwordx4 v[110:113], v[84:85], off offset:1536
	v_add_u32_e32 v84, s2, v147
	ds_read_b128 v[118:121], v153 offset:33792
	v_ashrrev_i32_e32 v85, 31, v84
	v_lshlrev_b64 v[84:85], 11, v[84:85]
	v_lshl_add_u64 v[82:83], v[82:83], 0, v[84:85]
	v_or_b32_e32 v0, s2, v148
	global_load_dwordx4 v[114:117], v[82:83], off offset:1536
	v_lshl_add_u64 v[82:83], v[140:141], 0, s[0:1]
	v_lshlrev_b32_e32 v0, 11, v0
	v_lshl_add_u64 v[94:95], v[82:83], 0, v[0:1]
	v_add_co_u32_e32 v86, vcc, s97, v94
	s_nop 0
	v_addc_co_u32_e32 v87, vcc, 0, v95, vcc
	v_add_co_u32_e32 v90, vcc, s4, v94
	v_addc_co_u32_e32 v91, vcc, 0, v95, vcc
	global_load_dwordx4 v[82:85], v[94:95], off offset:1536
	v_add_co_u32_e32 v94, vcc, s96, v94
	v_addc_co_u32_e32 v95, vcc, 0, v95, vcc
	global_load_dwordx4 v[86:89], v[86:87], off offset:1536
	global_load_dwordx4 v[90:93], v[90:91], off offset:1536
	global_load_dwordx4 v[94:97], v[94:95], off offset:1536
	v_add_u32_e32 v157, 64, v157
	v_lshl_add_u32 v224, v134, 3, v135
	v_mul_u32_u24_e32 v224, 0x210, v224
	v_lshl_add_u32 v224, v136, 3, v224
	v_lshl_add_u32 v224, v137, 6, v224
	v_add_u32_e32 v225, 16, v226
	v_mul_u32_u24_e32 v225, 0x210, v225
	v_lshl_add_u32 v225, v134, 3, v225
	v_lshl_add_u32 v225, v137, 6, v225
	v_lshlrev_b32_e32 v135, 3, v134
	v_sub_u32_e32 v135, v135, v226
	v_add_u32_e32 v135, -1, v135
	v_mov_b32_e32 v216, 0x3f80
	v_add_u32_e32 v217, 0, v135
	v_and_b32_e32 v217, -16, v217
	v_min_u32_e32 v217, 1, v217
	v_sub_u32_e32 v217, 1, v217
	v_mul_u32_u24_e32 v217, v217, v216
	v_add_u32_e32 v218, 1, v135
	v_and_b32_e32 v218, -16, v218
	v_min_u32_e32 v218, 1, v218
	v_sub_u32_e32 v218, 1, v218
	v_mul_u32_u24_e32 v218, v218, v216
	v_lshl_or_b32 v190, v218, 16, v217
	v_add_u32_e32 v217, 2, v135
	v_and_b32_e32 v217, -16, v217
	v_min_u32_e32 v217, 1, v217
	v_sub_u32_e32 v217, 1, v217
	v_mul_u32_u24_e32 v217, v217, v216
	v_add_u32_e32 v218, 3, v135
	v_and_b32_e32 v218, -16, v218
	v_min_u32_e32 v218, 1, v218
	v_sub_u32_e32 v218, 1, v218
	v_mul_u32_u24_e32 v218, v218, v216
	v_lshl_or_b32 v191, v218, 16, v217
	v_add_u32_e32 v217, 4, v135
	v_and_b32_e32 v217, -16, v217
	v_min_u32_e32 v217, 1, v217
	v_sub_u32_e32 v217, 1, v217
	v_mul_u32_u24_e32 v217, v217, v216
	v_add_u32_e32 v218, 5, v135
	v_and_b32_e32 v218, -16, v218
	v_min_u32_e32 v218, 1, v218
	v_sub_u32_e32 v218, 1, v218
	v_mul_u32_u24_e32 v218, v218, v216
	v_lshl_or_b32 v192, v218, 16, v217
	v_add_u32_e32 v217, 6, v135
	v_and_b32_e32 v217, -16, v217
	v_min_u32_e32 v217, 1, v217
	v_sub_u32_e32 v217, 1, v217
	v_mul_u32_u24_e32 v217, v217, v216
	v_add_u32_e32 v218, 7, v135
	v_and_b32_e32 v218, -16, v218
	v_min_u32_e32 v218, 1, v218
	v_sub_u32_e32 v218, 1, v218
	v_mul_u32_u24_e32 v218, v218, v216
	v_lshl_or_b32 v193, v218, 16, v217
	ds_read_b64_tr_b16 v[200:201], v224 offset:0
	ds_read_b64_tr_b16 v[202:203], v224 offset:2112
	ds_read_b64_tr_b16 v[204:205], v224 offset:8448
	ds_read_b64_tr_b16 v[206:207], v224 offset:10560
	ds_read_b64_tr_b16 v[208:209], v224 offset:16896
	ds_read_b64_tr_b16 v[210:211], v224 offset:19008
	ds_read_b64_tr_b16 v[212:213], v224 offset:25344
	ds_read_b64_tr_b16 v[214:215], v224 offset:27456
	ds_read_b64 v[216:217], v225 offset:0
	ds_read_b64 v[218:219], v225 offset:8448
	ds_read_b64 v[220:221], v225 offset:16896
	ds_read_b64 v[222:223], v225 offset:25344
	s_waitcnt lgkmcnt(4)
	v_mfma_f32_16x16x32_bf16 v[160:163], v[200:203], v[190:193], 0
	v_mfma_f32_16x16x32_bf16 v[164:167], v[204:207], v[190:193], 0
	v_mfma_f32_16x16x32_bf16 v[172:175], v[208:211], v[190:193], 0
	v_mfma_f32_16x16x32_bf16 v[176:179], v[212:215], v[190:193], 0
	s_waitcnt lgkmcnt(0)
	v_add_u32_e32 v227, s66, v226
	v_min_i32_e32 v227, 15, v227
	v_add_u32_e32 v227, 1, v227
	v_cvt_f32_i32_e32 v227, v227
	v_rcp_iflag_f32_e32 v227, v227
	v_lshlrev_b32_e32 v134, 16, v216
	v_and_b32_e32 v135, 0xffff0000, v216
	v_lshlrev_b32_e32 v136, 16, v217
	v_and_b32_e32 v137, 0xffff0000, v217
	s_nop 7
	v_fma_f32 v134, v160, v227, -v134
	v_fma_f32 v135, v161, v227, -v135
	v_fma_f32 v136, v162, v227, -v136
	v_fma_f32 v137, v163, v227, -v137
	v_cvt_pk_bf16_f32 v180, v134, v135
	v_cvt_pk_bf16_f32 v181, v136, v137
	s_nop 0
	ds_write_b64 v225, v[180:181] offset:33792
	v_add_u32_e32 v227, s66, v226
	v_add_u32_e32 v227, 16, v227
	v_min_i32_e32 v227, 15, v227
	v_add_u32_e32 v227, 1, v227
	v_cvt_f32_i32_e32 v227, v227
	v_rcp_iflag_f32_e32 v227, v227
	v_lshlrev_b32_e32 v134, 16, v218
	v_and_b32_e32 v135, 0xffff0000, v218
	v_lshlrev_b32_e32 v136, 16, v219
	v_and_b32_e32 v137, 0xffff0000, v219
	v_fma_f32 v134, v164, v227, -v134
	v_fma_f32 v135, v165, v227, -v135
	v_fma_f32 v136, v166, v227, -v136
	v_fma_f32 v137, v167, v227, -v137
	v_cvt_pk_bf16_f32 v180, v134, v135
	v_cvt_pk_bf16_f32 v181, v136, v137
	s_nop 0
	ds_write_b64 v225, v[180:181] offset:42240
	v_add_u32_e32 v227, s66, v226
	v_add_u32_e32 v227, 32, v227
	v_min_i32_e32 v227, 15, v227
	v_add_u32_e32 v227, 1, v227
	v_cvt_f32_i32_e32 v227, v227
	v_rcp_iflag_f32_e32 v227, v227
	v_lshlrev_b32_e32 v134, 16, v220
	v_and_b32_e32 v135, 0xffff0000, v220
	v_lshlrev_b32_e32 v136, 16, v221
	v_and_b32_e32 v137, 0xffff0000, v221
	v_fma_f32 v134, v172, v227, -v134
	v_fma_f32 v135, v173, v227, -v135
	v_fma_f32 v136, v174, v227, -v136
	v_fma_f32 v137, v175, v227, -v137
	v_cvt_pk_bf16_f32 v180, v134, v135
	v_cvt_pk_bf16_f32 v181, v136, v137
	s_nop 0
	ds_write_b64 v225, v[180:181] offset:50688
	v_add_u32_e32 v227, s66, v226
	v_add_u32_e32 v227, 48, v227
	v_min_i32_e32 v227, 15, v227
	v_add_u32_e32 v227, 1, v227
	v_cvt_f32_i32_e32 v227, v227
	v_rcp_iflag_f32_e32 v227, v227
	v_lshlrev_b32_e32 v134, 16, v222
	v_and_b32_e32 v135, 0xffff0000, v222
	v_lshlrev_b32_e32 v136, 16, v223
	v_and_b32_e32 v137, 0xffff0000, v223
	v_fma_f32 v134, v176, v227, -v134
	v_fma_f32 v135, v177, v227, -v135
	v_fma_f32 v136, v178, v227, -v136
	v_fma_f32 v137, v179, v227, -v137
	v_cvt_pk_bf16_f32 v180, v134, v135
	v_cvt_pk_bf16_f32 v181, v136, v137
	s_nop 0
	ds_write_b64 v225, v[180:181] offset:59136
	s_waitcnt lgkmcnt(0)
	ds_read_b64_tr_b16 v[200:201], v224 offset:32
	ds_read_b64_tr_b16 v[202:203], v224 offset:2144
	ds_read_b64_tr_b16 v[204:205], v224 offset:8480
	ds_read_b64_tr_b16 v[206:207], v224 offset:10592
	ds_read_b64_tr_b16 v[208:209], v224 offset:16928
	ds_read_b64_tr_b16 v[210:211], v224 offset:19040
	ds_read_b64_tr_b16 v[212:213], v224 offset:25376
	ds_read_b64_tr_b16 v[214:215], v224 offset:27488
	ds_read_b64 v[216:217], v225 offset:32
	ds_read_b64 v[218:219], v225 offset:8480
	ds_read_b64 v[220:221], v225 offset:16928
	ds_read_b64 v[222:223], v225 offset:25376
	s_waitcnt lgkmcnt(4)
	v_mfma_f32_16x16x32_bf16 v[160:163], v[200:203], v[190:193], 0
	v_mfma_f32_16x16x32_bf16 v[164:167], v[204:207], v[190:193], 0
	v_mfma_f32_16x16x32_bf16 v[172:175], v[208:211], v[190:193], 0
	v_mfma_f32_16x16x32_bf16 v[176:179], v[212:215], v[190:193], 0
	s_waitcnt lgkmcnt(0)
	v_add_u32_e32 v227, s66, v226
	v_min_i32_e32 v227, 15, v227
	v_add_u32_e32 v227, 1, v227
	v_cvt_f32_i32_e32 v227, v227
	v_rcp_iflag_f32_e32 v227, v227
	v_lshlrev_b32_e32 v134, 16, v216
	v_and_b32_e32 v135, 0xffff0000, v216
	v_lshlrev_b32_e32 v136, 16, v217
	v_and_b32_e32 v137, 0xffff0000, v217
	s_nop 7
	v_fma_f32 v134, v160, v227, -v134
	v_fma_f32 v135, v161, v227, -v135
	v_fma_f32 v136, v162, v227, -v136
	v_fma_f32 v137, v163, v227, -v137
	v_cvt_pk_bf16_f32 v180, v134, v135
	v_cvt_pk_bf16_f32 v181, v136, v137
	s_nop 0
	ds_write_b64 v225, v[180:181] offset:33824
	v_add_u32_e32 v227, s66, v226
	v_add_u32_e32 v227, 16, v227
	v_min_i32_e32 v227, 15, v227
	v_add_u32_e32 v227, 1, v227
	v_cvt_f32_i32_e32 v227, v227
	v_rcp_iflag_f32_e32 v227, v227
	v_lshlrev_b32_e32 v134, 16, v218
	v_and_b32_e32 v135, 0xffff0000, v218
	v_lshlrev_b32_e32 v136, 16, v219
	v_and_b32_e32 v137, 0xffff0000, v219
	v_fma_f32 v134, v164, v227, -v134
	v_fma_f32 v135, v165, v227, -v135
	v_fma_f32 v136, v166, v227, -v136
	v_fma_f32 v137, v167, v227, -v137
	v_cvt_pk_bf16_f32 v180, v134, v135
	v_cvt_pk_bf16_f32 v181, v136, v137
	s_nop 0
	ds_write_b64 v225, v[180:181] offset:42272
	v_add_u32_e32 v227, s66, v226
	v_add_u32_e32 v227, 32, v227
	v_min_i32_e32 v227, 15, v227
	v_add_u32_e32 v227, 1, v227
	v_cvt_f32_i32_e32 v227, v227
	v_rcp_iflag_f32_e32 v227, v227
	v_lshlrev_b32_e32 v134, 16, v220
	v_and_b32_e32 v135, 0xffff0000, v220
	v_lshlrev_b32_e32 v136, 16, v221
	v_and_b32_e32 v137, 0xffff0000, v221
	v_fma_f32 v134, v172, v227, -v134
	v_fma_f32 v135, v173, v227, -v135
	v_fma_f32 v136, v174, v227, -v136
	v_fma_f32 v137, v175, v227, -v137
	v_cvt_pk_bf16_f32 v180, v134, v135
	v_cvt_pk_bf16_f32 v181, v136, v137
	s_nop 0
	ds_write_b64 v225, v[180:181] offset:50720
	v_add_u32_e32 v227, s66, v226
	v_add_u32_e32 v227, 48, v227
	v_min_i32_e32 v227, 15, v227
	v_add_u32_e32 v227, 1, v227
	v_cvt_f32_i32_e32 v227, v227
	v_rcp_iflag_f32_e32 v227, v227
	v_lshlrev_b32_e32 v134, 16, v222
	v_and_b32_e32 v135, 0xffff0000, v222
	v_lshlrev_b32_e32 v136, 16, v223
	v_and_b32_e32 v137, 0xffff0000, v223
	v_fma_f32 v134, v176, v227, -v134
	v_fma_f32 v135, v177, v227, -v135
	v_fma_f32 v136, v178, v227, -v136
	v_fma_f32 v137, v179, v227, -v137
	v_cvt_pk_bf16_f32 v180, v134, v135
	v_cvt_pk_bf16_f32 v181, v136, v137
	s_nop 0
	ds_write_b64 v225, v[180:181] offset:59168
	s_waitcnt lgkmcnt(0)
	s_barrier
	ds_read_b128 v[134:137], v155 offset:42240
	ds_read_b128 v[164:167], v155 offset:42304
	ds_read_b128 v[238:241], v155 offset:42368
	ds_read_b128 v[242:245], v155 offset:42432
	ds_read_b128 v[246:249], v155 offset:42496
	ds_read_b128 v[228:231], v155 offset:42560
	s_waitcnt lgkmcnt(5)
	v_mfma_f32_16x16x32_bf16 v[160:163], v[2:5], v[134:137], 0
	v_mfma_f32_16x16x32_bf16 v[134:137], v[34:37], v[134:137], 0
	s_waitcnt lgkmcnt(4)
	v_mfma_f32_16x16x32_bf16 v[160:163], v[6:9], v[164:167], v[160:163]
	v_mfma_f32_16x16x32_bf16 v[134:137], v[38:41], v[164:167], v[134:137]
	ds_read_b128 v[164:167], v155 offset:42624
	s_waitcnt lgkmcnt(4)
	v_mfma_f32_16x16x32_bf16 v[160:163], v[10:13], v[238:241], v[160:163]
	v_mfma_f32_16x16x32_bf16 v[134:137], v[42:45], v[238:241], v[134:137]
	ds_read_b128 v[238:241], v155 offset:42688
	s_waitcnt lgkmcnt(4)
	v_mfma_f32_16x16x32_bf16 v[160:163], v[14:17], v[242:245], v[160:163]
	v_mfma_f32_16x16x32_bf16 v[134:137], v[46:49], v[242:245], v[134:137]
	s_waitcnt lgkmcnt(3)
	v_mfma_f32_16x16x32_bf16 v[160:163], v[18:21], v[246:249], v[160:163]
	v_mfma_f32_16x16x32_bf16 v[134:137], v[50:53], v[246:249], v[134:137]
	s_waitcnt lgkmcnt(2)
	v_mfma_f32_16x16x32_bf16 v[160:163], v[22:25], v[228:231], v[160:163]
	v_mfma_f32_16x16x32_bf16 v[134:137], v[54:57], v[228:231], v[134:137]
	s_waitcnt lgkmcnt(1)
	v_mfma_f32_16x16x32_bf16 v[160:163], v[26:29], v[164:167], v[160:163]
	v_mfma_f32_16x16x32_bf16 v[134:137], v[58:61], v[164:167], v[134:137]
	s_waitcnt lgkmcnt(0)
	v_mfma_f32_16x16x32_bf16 v[160:163], v[30:33], v[238:241], v[160:163]
	v_mfma_f32_16x16x32_bf16 v[134:137], v[62:65], v[238:241], v[134:137]
	s_nop 6
	v_add_f32_e32 v163, v73, v163
	v_add_f32_e32 v0, v72, v162
	v_and_b32_e32 v162, 0xffff0000, v131
	v_add_f32_e32 v159, v71, v161
	v_mul_f32_e32 v161, v81, v163
	v_mul_f32_e32 v163, 0xbfb8aa3b, v162
	v_exp_f32_e32 v163, v163
	v_add_f32_e32 v160, v70, v160
	v_mul_f32_e32 v160, v78, v160
	v_mul_f32_e32 v159, v79, v159
	v_add_f32_e32 v163, 1.0, v163
	v_rcp_f32_e32 v163, v163
	v_lshlrev_b32_e32 v131, 16, v131
	v_mul_f32_e32 v0, v80, v0
	v_add_f32_e32 v134, v66, v134
	v_mul_f32_e32 v162, v163, v162
	v_mul_f32_e32 v161, v162, v161
	v_lshlrev_b32_e32 v162, 16, v130
	v_mul_f32_e32 v163, 0xbfb8aa3b, v162
	v_exp_f32_e32 v163, v163
	v_and_b32_e32 v130, 0xffff0000, v130
	v_mul_f32_e32 v134, v74, v134
	v_add_f32_e32 v135, v67, v135
	v_add_f32_e32 v163, 1.0, v163
	v_rcp_f32_e32 v163, v163
	v_mul_f32_e32 v135, v75, v135
	v_add_f32_e32 v136, v68, v136
	v_mul_f32_e32 v136, v76, v136
	v_mul_f32_e32 v162, v163, v162
	v_mul_f32_e32 v160, v162, v160
	v_mul_f32_e32 v162, 0xbfb8aa3b, v130
	v_exp_f32_e32 v162, v162
	s_nop 0
	v_add_f32_e32 v162, 1.0, v162
	v_rcp_f32_e32 v162, v162
	s_nop 0
	v_mul_f32_e32 v130, v162, v130
	v_mul_f32_e32 v130, v130, v159
	v_mul_f32_e32 v159, 0xbfb8aa3b, v131
	v_exp_f32_e32 v159, v159
	v_cvt_pk_bf16_f32 v130, v160, v130
	s_nop 0
	v_add_f32_e32 v159, 1.0, v159
	v_rcp_f32_e32 v159, v159
	s_nop 0
	v_mul_f32_e32 v131, v159, v131
	v_mul_f32_e32 v0, v131, v0
	v_cvt_pk_bf16_f32 v131, v0, v161
	v_add_f32_e32 v0, v69, v137
	v_and_b32_e32 v137, 0xffff0000, v133
	v_mul_f32_e32 v159, 0xbfb8aa3b, v137
	v_exp_f32_e32 v159, v159
	v_mul_f32_e32 v0, v77, v0
	v_lshlrev_b32_e32 v133, 16, v133
	v_add_f32_e32 v159, 1.0, v159
	v_rcp_f32_e32 v159, v159
	s_nop 0
	v_mul_f32_e32 v137, v159, v137
	v_mul_f32_e32 v0, v137, v0
	v_lshlrev_b32_e32 v137, 16, v132
	v_mul_f32_e32 v159, 0xbfb8aa3b, v137
	v_exp_f32_e32 v159, v159
	v_and_b32_e32 v132, 0xffff0000, v132
	v_add_f32_e32 v159, 1.0, v159
	v_rcp_f32_e32 v159, v159
	s_nop 0
	v_mul_f32_e32 v137, v159, v137
	v_mul_f32_e32 v134, v137, v134
	v_mul_f32_e32 v137, 0xbfb8aa3b, v132
	v_exp_f32_e32 v137, v137
	s_nop 0
	v_add_f32_e32 v137, 1.0, v137
	v_rcp_f32_e32 v137, v137
	s_nop 0
	v_mul_f32_e32 v132, v137, v132
	v_mul_f32_e32 v132, v132, v135
	v_mul_f32_e32 v135, 0xbfb8aa3b, v133
	v_exp_f32_e32 v135, v135
	v_cvt_pk_bf16_f32 v132, v134, v132
	s_nop 0
	v_add_f32_e32 v135, 1.0, v135
	v_rcp_f32_e32 v135, v135
	s_nop 0
	v_mul_f32_e32 v133, v135, v133
	v_lshl_add_u64 v[134:135], v[142:143], 0, s[42:43]
	v_mul_f32_e32 v133, v133, v136
	v_add_co_u32_e32 v136, vcc, s9, v134
	v_cvt_pk_bf16_f32 v133, v133, v0
	ds_read_b128 v[164:167], v155 offset:50752
	s_nop 0
	v_addc_co_u32_e32 v137, vcc, 0, v135, vcc
	global_store_dwordx4 v[136:137], v[130:133], off offset:3584
	ds_read_b128 v[130:133], v155 offset:50688
	ds_read_b128 v[238:241], v155 offset:50816
	ds_read_b128 v[242:245], v155 offset:50880
	ds_read_b128 v[246:249], v155 offset:50944
	ds_read_b128 v[228:231], v155 offset:51008
	s_waitcnt lgkmcnt(4)
	v_mfma_f32_16x16x32_bf16 v[160:163], v[2:5], v[130:133], 0
	s_add_u32 s42, s42, 0x40000
	s_addc_u32 s43, s43, 0
	s_add_i32 s11, s11, 1
	v_mfma_f32_16x16x32_bf16 v[130:133], v[34:37], v[130:133], 0
	s_cmp_lg_u32 s42, 0x200000
	s_waitcnt lgkmcnt(5)
	v_mfma_f32_16x16x32_bf16 v[160:163], v[6:9], v[164:167], v[160:163]
	v_mfma_f32_16x16x32_bf16 v[130:133], v[38:41], v[164:167], v[130:133]
	ds_read_b128 v[164:167], v155 offset:51072
	s_waitcnt lgkmcnt(4)
	v_mfma_f32_16x16x32_bf16 v[160:163], v[10:13], v[238:241], v[160:163]
	v_mfma_f32_16x16x32_bf16 v[130:133], v[42:45], v[238:241], v[130:133]
	ds_read_b128 v[238:241], v155 offset:51136
	s_waitcnt lgkmcnt(4)
	v_mfma_f32_16x16x32_bf16 v[160:163], v[14:17], v[242:245], v[160:163]
	v_mfma_f32_16x16x32_bf16 v[130:133], v[46:49], v[242:245], v[130:133]
	s_waitcnt lgkmcnt(3)
	v_mfma_f32_16x16x32_bf16 v[160:163], v[18:21], v[246:249], v[160:163]
	v_mfma_f32_16x16x32_bf16 v[130:133], v[50:53], v[246:249], v[130:133]
	s_waitcnt lgkmcnt(2)
	v_mfma_f32_16x16x32_bf16 v[160:163], v[22:25], v[228:231], v[160:163]
	v_mfma_f32_16x16x32_bf16 v[130:133], v[54:57], v[228:231], v[130:133]
	s_waitcnt lgkmcnt(1)
	v_mfma_f32_16x16x32_bf16 v[160:163], v[26:29], v[164:167], v[160:163]
	v_mfma_f32_16x16x32_bf16 v[130:133], v[58:61], v[164:167], v[130:133]
	s_waitcnt lgkmcnt(0)
	v_mfma_f32_16x16x32_bf16 v[160:163], v[30:33], v[238:241], v[160:163]
	v_mfma_f32_16x16x32_bf16 v[130:133], v[62:65], v[238:241], v[130:133]
	s_nop 6
	v_add_f32_e32 v136, v70, v160
	v_and_b32_e32 v160, 0xffff0000, v127
	v_add_f32_e32 v137, v71, v161
	v_mul_f32_e32 v161, 0xbfb8aa3b, v160
	v_exp_f32_e32 v161, v161
	v_add_f32_e32 v0, v73, v163
	v_mul_f32_e32 v0, v81, v0
	v_mul_f32_e32 v136, v78, v136
	v_add_f32_e32 v161, 1.0, v161
	v_rcp_f32_e32 v161, v161
	v_mul_f32_e32 v137, v79, v137
	v_lshlrev_b32_e32 v127, 16, v127
	v_add_f32_e32 v159, v72, v162
	v_mul_f32_e32 v160, v161, v160
	v_mul_f32_e32 v0, v160, v0
	v_lshlrev_b32_e32 v160, 16, v126
	v_mul_f32_e32 v161, 0xbfb8aa3b, v160
	v_exp_f32_e32 v161, v161
	v_and_b32_e32 v126, 0xffff0000, v126
	v_mul_f32_e32 v159, v80, v159
	v_add_f32_e32 v130, v66, v130
	v_add_f32_e32 v161, 1.0, v161
	v_rcp_f32_e32 v161, v161
	v_mul_f32_e32 v130, v74, v130
	v_add_f32_e32 v131, v67, v131
	v_mul_f32_e32 v131, v75, v131
	v_mul_f32_e32 v160, v161, v160
	v_mul_f32_e32 v136, v160, v136
	v_mul_f32_e32 v160, 0xbfb8aa3b, v126
	v_exp_f32_e32 v160, v160
	v_add_f32_e32 v132, v68, v132
	v_mul_f32_e32 v132, v76, v132
	v_add_f32_e32 v160, 1.0, v160
	v_rcp_f32_e32 v160, v160
	s_nop 0
	v_mul_f32_e32 v126, v160, v126
	v_mul_f32_e32 v126, v126, v137
	v_mul_f32_e32 v137, 0xbfb8aa3b, v127
	v_exp_f32_e32 v137, v137
	v_cvt_pk_bf16_f32 v126, v136, v126
	s_nop 0
	v_add_f32_e32 v137, 1.0, v137
	v_rcp_f32_e32 v137, v137
	s_nop 0
	v_mul_f32_e32 v127, v137, v127
	v_mul_f32_e32 v127, v127, v159
	v_cvt_pk_bf16_f32 v127, v127, v0
	v_add_f32_e32 v0, v69, v133
	v_and_b32_e32 v133, 0xffff0000, v129
	v_mul_f32_e32 v136, 0xbfb8aa3b, v133
	v_exp_f32_e32 v136, v136
	v_mul_f32_e32 v0, v77, v0
	v_lshlrev_b32_e32 v129, 16, v129
	v_add_f32_e32 v136, 1.0, v136
	v_rcp_f32_e32 v136, v136
	s_nop 0
	v_mul_f32_e32 v133, v136, v133
	v_mul_f32_e32 v0, v133, v0
	v_lshlrev_b32_e32 v133, 16, v128
	v_mul_f32_e32 v136, 0xbfb8aa3b, v133
	v_exp_f32_e32 v136, v136
	v_and_b32_e32 v128, 0xffff0000, v128
	v_add_f32_e32 v136, 1.0, v136
	v_rcp_f32_e32 v136, v136
	s_nop 0
	v_mul_f32_e32 v133, v136, v133
	v_mul_f32_e32 v130, v133, v130
	v_mul_f32_e32 v133, 0xbfb8aa3b, v128
	v_exp_f32_e32 v133, v133
	s_nop 0
	v_add_f32_e32 v133, 1.0, v133
	v_rcp_f32_e32 v133, v133
	s_nop 0
	v_mul_f32_e32 v128, v133, v128
	v_mul_f32_e32 v128, v128, v131
	v_mul_f32_e32 v131, 0xbfb8aa3b, v129
	v_exp_f32_e32 v131, v131
	v_cvt_pk_bf16_f32 v128, v130, v128
	v_add_co_u32_e32 v130, vcc, s24, v134
	v_add_f32_e32 v131, 1.0, v131
	v_rcp_f32_e32 v131, v131
	s_nop 0
	v_mul_f32_e32 v129, v131, v129
	v_mul_f32_e32 v129, v129, v132
	v_cvt_pk_bf16_f32 v129, v129, v0
	v_addc_co_u32_e32 v131, vcc, 0, v135, vcc
	global_store_dwordx4 v[130:131], v[126:129], off offset:3584
	ds_read_b128 v[126:129], v155 offset:59136
	ds_read_b128 v[160:163], v155 offset:59200
	ds_read_b128 v[238:241], v155 offset:59264
	ds_read_b128 v[242:245], v155 offset:59328
	ds_read_b128 v[246:249], v155 offset:59392
	ds_read_b128 v[228:231], v155 offset:59456
	s_waitcnt lgkmcnt(5)
	v_mfma_f32_16x16x32_bf16 v[130:133], v[2:5], v[126:129], 0
	v_mfma_f32_16x16x32_bf16 v[126:129], v[34:37], v[126:129], 0
	s_waitcnt lgkmcnt(4)
	v_mfma_f32_16x16x32_bf16 v[130:133], v[6:9], v[160:163], v[130:133]
	v_mfma_f32_16x16x32_bf16 v[126:129], v[38:41], v[160:163], v[126:129]
	ds_read_b128 v[160:163], v155 offset:59520
	s_waitcnt lgkmcnt(4)
	v_mfma_f32_16x16x32_bf16 v[130:133], v[10:13], v[238:241], v[130:133]
	v_mfma_f32_16x16x32_bf16 v[126:129], v[42:45], v[238:241], v[126:129]
	ds_read_b128 v[238:241], v155 offset:59584
	s_waitcnt lgkmcnt(4)
	v_mfma_f32_16x16x32_bf16 v[130:133], v[14:17], v[242:245], v[130:133]
	v_mfma_f32_16x16x32_bf16 v[126:129], v[46:49], v[242:245], v[126:129]
	s_waitcnt lgkmcnt(3)
	v_mfma_f32_16x16x32_bf16 v[130:133], v[18:21], v[246:249], v[130:133]
	v_mfma_f32_16x16x32_bf16 v[126:129], v[50:53], v[246:249], v[126:129]
	s_waitcnt lgkmcnt(2)
	v_mfma_f32_16x16x32_bf16 v[130:133], v[22:25], v[228:231], v[130:133]
	v_mfma_f32_16x16x32_bf16 v[126:129], v[54:57], v[228:231], v[126:129]
	s_waitcnt lgkmcnt(1)
	v_mfma_f32_16x16x32_bf16 v[130:133], v[26:29], v[160:163], v[130:133]
	v_mfma_f32_16x16x32_bf16 v[126:129], v[58:61], v[160:163], v[126:129]
	s_waitcnt lgkmcnt(0)
	v_mfma_f32_16x16x32_bf16 v[130:133], v[30:33], v[238:241], v[130:133]
	v_mfma_f32_16x16x32_bf16 v[126:129], v[62:65], v[238:241], v[126:129]
	s_nop 6
	v_add_f32_e32 v0, v73, v133
	v_and_b32_e32 v133, 0xffff0000, v123
	v_mul_f32_e32 v136, 0xbfb8aa3b, v133
	v_exp_f32_e32 v136, v136
	v_mul_f32_e32 v0, v81, v0
	v_add_f32_e32 v130, v70, v130
	v_mul_f32_e32 v130, v78, v130
	v_add_f32_e32 v136, 1.0, v136
	v_rcp_f32_e32 v136, v136
	v_add_f32_e32 v131, v71, v131
	v_mul_f32_e32 v131, v79, v131
	v_lshlrev_b32_e32 v123, 16, v123
	v_mul_f32_e32 v133, v136, v133
	v_mul_f32_e32 v0, v133, v0
	v_lshlrev_b32_e32 v133, 16, v122
	v_mul_f32_e32 v136, 0xbfb8aa3b, v133
	v_exp_f32_e32 v136, v136
	v_and_b32_e32 v122, 0xffff0000, v122
	v_add_f32_e32 v132, v72, v132
	v_mul_f32_e32 v132, v80, v132
	v_add_f32_e32 v136, 1.0, v136
	v_rcp_f32_e32 v136, v136
	v_add_f32_e32 v126, v66, v126
	v_mul_f32_e32 v126, v74, v126
	v_add_f32_e32 v127, v67, v127
	v_mul_f32_e32 v133, v136, v133
	v_mul_f32_e32 v130, v133, v130
	v_mul_f32_e32 v133, 0xbfb8aa3b, v122
	v_exp_f32_e32 v133, v133
	v_mul_f32_e32 v127, v75, v127
	v_add_f32_e32 v128, v68, v128
	v_mul_f32_e32 v128, v76, v128
	v_add_f32_e32 v133, 1.0, v133
	v_rcp_f32_e32 v133, v133
	s_nop 0
	v_mul_f32_e32 v122, v133, v122
	v_mul_f32_e32 v122, v122, v131
	v_mul_f32_e32 v131, 0xbfb8aa3b, v123
	v_exp_f32_e32 v131, v131
	v_cvt_pk_bf16_f32 v122, v130, v122
	s_nop 0
	v_add_f32_e32 v131, 1.0, v131
	v_rcp_f32_e32 v131, v131
	s_nop 0
	v_mul_f32_e32 v123, v131, v123
	v_mul_f32_e32 v123, v123, v132
	v_cvt_pk_bf16_f32 v123, v123, v0
	v_add_f32_e32 v0, v69, v129
	v_and_b32_e32 v129, 0xffff0000, v125
	v_mul_f32_e32 v130, 0xbfb8aa3b, v129
	v_exp_f32_e32 v130, v130
	v_mul_f32_e32 v0, v77, v0
	v_lshlrev_b32_e32 v125, 16, v125
	v_add_f32_e32 v130, 1.0, v130
	v_rcp_f32_e32 v130, v130
	s_nop 0
	v_mul_f32_e32 v129, v130, v129
	v_mul_f32_e32 v0, v129, v0
	v_lshlrev_b32_e32 v129, 16, v124
	v_mul_f32_e32 v130, 0xbfb8aa3b, v129
	v_exp_f32_e32 v130, v130
	v_and_b32_e32 v124, 0xffff0000, v124
	v_add_f32_e32 v130, 1.0, v130
	v_rcp_f32_e32 v130, v130
	s_nop 0
	v_mul_f32_e32 v129, v130, v129
	v_mul_f32_e32 v126, v129, v126
	v_mul_f32_e32 v129, 0xbfb8aa3b, v124
	v_exp_f32_e32 v129, v129
	s_nop 0
	v_add_f32_e32 v129, 1.0, v129
	v_rcp_f32_e32 v129, v129
	s_nop 0
	v_mul_f32_e32 v124, v129, v124
	v_mul_f32_e32 v124, v124, v127
	v_mul_f32_e32 v127, 0xbfb8aa3b, v125
	v_exp_f32_e32 v127, v127
	v_cvt_pk_bf16_f32 v124, v126, v124
	v_add_co_u32_e32 v126, vcc, s25, v134
	v_add_f32_e32 v127, 1.0, v127
	v_rcp_f32_e32 v127, v127
	s_nop 0
	v_mul_f32_e32 v125, v127, v125
	v_mul_f32_e32 v125, v125, v128
	v_cvt_pk_bf16_f32 v125, v125, v0
	v_addc_co_u32_e32 v127, vcc, 0, v135, vcc
	global_store_dwordx4 v[126:127], v[122:125], off offset:3584
	ds_read_b128 v[122:125], v156 offset:25344
	ds_read_b128 v[130:133], v156 offset:25408
	ds_read_b128 v[238:241], v156 offset:25472
	ds_read_b128 v[242:245], v156 offset:25536
	ds_read_b128 v[246:249], v156 offset:25600
	ds_read_b128 v[228:231], v156 offset:25664
	s_waitcnt lgkmcnt(5)
	v_mfma_f32_16x16x32_bf16 v[126:129], v[2:5], v[122:125], 0
	v_mfma_f32_16x16x32_bf16 v[122:125], v[34:37], v[122:125], 0
	s_waitcnt lgkmcnt(4)
	v_mfma_f32_16x16x32_bf16 v[126:129], v[6:9], v[130:133], v[126:129]
	v_mfma_f32_16x16x32_bf16 v[122:125], v[38:41], v[130:133], v[122:125]
	ds_read_b128 v[130:133], v156 offset:25728
	s_waitcnt lgkmcnt(4)
	v_mfma_f32_16x16x32_bf16 v[126:129], v[10:13], v[238:241], v[126:129]
	v_mfma_f32_16x16x32_bf16 v[122:125], v[42:45], v[238:241], v[122:125]
	ds_read_b128 v[238:241], v156 offset:25792
	s_waitcnt lgkmcnt(4)
	v_mfma_f32_16x16x32_bf16 v[126:129], v[14:17], v[242:245], v[126:129]
	v_mfma_f32_16x16x32_bf16 v[122:125], v[46:49], v[242:245], v[122:125]
	s_waitcnt lgkmcnt(3)
	v_mfma_f32_16x16x32_bf16 v[126:129], v[18:21], v[246:249], v[126:129]
	v_mfma_f32_16x16x32_bf16 v[122:125], v[50:53], v[246:249], v[122:125]
	s_waitcnt lgkmcnt(2)
	v_mfma_f32_16x16x32_bf16 v[126:129], v[22:25], v[228:231], v[126:129]
	v_mfma_f32_16x16x32_bf16 v[122:125], v[54:57], v[228:231], v[122:125]
	s_waitcnt lgkmcnt(1)
	v_mfma_f32_16x16x32_bf16 v[126:129], v[26:29], v[130:133], v[126:129]
	v_mfma_f32_16x16x32_bf16 v[122:125], v[58:61], v[130:133], v[122:125]
	s_waitcnt lgkmcnt(0)
	v_mfma_f32_16x16x32_bf16 v[126:129], v[30:33], v[238:241], v[126:129]
	v_mfma_f32_16x16x32_bf16 v[122:125], v[62:65], v[238:241], v[122:125]
	s_nop 6
	v_add_f32_e32 v0, v73, v129
	v_and_b32_e32 v129, 0xffff0000, v99
	v_mul_f32_e32 v130, 0xbfb8aa3b, v129
	v_exp_f32_e32 v130, v130
	v_mul_f32_e32 v0, v81, v0
	v_add_f32_e32 v126, v70, v126
	v_mul_f32_e32 v126, v78, v126
	v_add_f32_e32 v130, 1.0, v130
	v_rcp_f32_e32 v130, v130
	v_add_f32_e32 v127, v71, v127
	v_mul_f32_e32 v127, v79, v127
	v_lshlrev_b32_e32 v99, 16, v99
	v_mul_f32_e32 v129, v130, v129
	v_mul_f32_e32 v0, v129, v0
	v_lshlrev_b32_e32 v129, 16, v98
	v_mul_f32_e32 v130, 0xbfb8aa3b, v129
	v_exp_f32_e32 v130, v130
	v_and_b32_e32 v98, 0xffff0000, v98
	v_add_f32_e32 v128, v72, v128
	v_mul_f32_e32 v128, v80, v128
	v_add_f32_e32 v130, 1.0, v130
	v_rcp_f32_e32 v130, v130
	v_add_f32_e32 v122, v66, v122
	v_mul_f32_e32 v122, v74, v122
	v_add_f32_e32 v123, v67, v123
	v_mul_f32_e32 v129, v130, v129
	v_mul_f32_e32 v126, v129, v126
	v_mul_f32_e32 v129, 0xbfb8aa3b, v98
	v_exp_f32_e32 v129, v129
	v_mul_f32_e32 v123, v75, v123
	v_add_f32_e32 v124, v68, v124
	v_mul_f32_e32 v124, v76, v124
	v_add_f32_e32 v129, 1.0, v129
	v_rcp_f32_e32 v129, v129
	s_waitcnt vmcnt(6)
	v_mov_b64_e32 v[132:133], v[84:85]
	v_mov_b64_e32 v[130:131], v[82:83]
	v_mul_f32_e32 v98, v129, v98
	v_mul_f32_e32 v98, v98, v127
	v_mul_f32_e32 v127, 0xbfb8aa3b, v99
	v_exp_f32_e32 v127, v127
	v_cvt_pk_bf16_f32 v98, v126, v98
	s_nop 0
	v_add_f32_e32 v127, 1.0, v127
	v_rcp_f32_e32 v127, v127
	s_nop 0
	v_mul_f32_e32 v99, v127, v99
	v_mul_f32_e32 v99, v99, v128
	v_cvt_pk_bf16_f32 v99, v99, v0
	v_add_f32_e32 v0, v69, v125
	v_and_b32_e32 v125, 0xffff0000, v101
	v_mul_f32_e32 v126, 0xbfb8aa3b, v125
	v_exp_f32_e32 v126, v126
	v_mul_f32_e32 v0, v77, v0
	v_lshlrev_b32_e32 v101, 16, v101
	v_add_f32_e32 v126, 1.0, v126
	v_rcp_f32_e32 v126, v126
	s_nop 0
	v_mul_f32_e32 v125, v126, v125
	v_mul_f32_e32 v0, v125, v0
	v_lshlrev_b32_e32 v125, 16, v100
	v_mul_f32_e32 v126, 0xbfb8aa3b, v125
	v_exp_f32_e32 v126, v126
	v_and_b32_e32 v100, 0xffff0000, v100
	v_add_f32_e32 v126, 1.0, v126
	v_rcp_f32_e32 v126, v126
	s_nop 0
	v_mul_f32_e32 v125, v126, v125
	v_mul_f32_e32 v122, v125, v122
	v_mul_f32_e32 v125, 0xbfb8aa3b, v100
	v_exp_f32_e32 v125, v125
	s_waitcnt vmcnt(5)
	v_mov_b64_e32 v[128:129], v[88:89]
	v_mov_b64_e32 v[126:127], v[86:87]
	v_add_f32_e32 v125, 1.0, v125
	v_rcp_f32_e32 v125, v125
	s_nop 0
	v_mul_f32_e32 v100, v125, v100
	v_mul_f32_e32 v100, v100, v123
	v_mul_f32_e32 v123, 0xbfb8aa3b, v101
	v_exp_f32_e32 v123, v123
	v_cvt_pk_bf16_f32 v100, v122, v100
	v_add_co_u32_e32 v122, vcc, s14, v134
	v_add_f32_e32 v123, 1.0, v123
	v_rcp_f32_e32 v123, v123
	s_nop 0
	v_mul_f32_e32 v101, v123, v101
	v_mul_f32_e32 v101, v101, v124
	v_cvt_pk_bf16_f32 v101, v101, v0
	v_addc_co_u32_e32 v123, vcc, 0, v135, vcc
	global_store_dwordx4 v[122:123], v[98:101], off offset:3584
	s_waitcnt vmcnt(5)
	v_mov_b64_e32 v[124:125], v[92:93]
	v_mov_b64_e32 v[122:123], v[90:91]
	s_waitcnt vmcnt(4)
	v_mov_b64_e32 v[100:101], v[96:97]
	v_mov_b64_e32 v[98:99], v[94:95]
	ds_write_b128 v149, v[102:105] offset:8448
	ds_write_b128 v150, v[106:109] offset:8448
	ds_write_b128 v151, v[110:113] offset:8448
	ds_write_b128 v152, v[114:117] offset:8448
	ds_write_b128 v153, v[118:121]
	s_cbranch_scc1 .LBB0_124
	s_waitcnt lgkmcnt(0)
	s_barrier
	s_mov_b64 s[0:1], 0
